# GEMM prologue: five of the six second-batch tile loads issued before the first wait (vmcnt 2 -> 7)
# speedup vs baseline: 1.0092x; 1.0092x over previous
; #define PG8_STAGE(bufoff, gbase, voff) do { _Pragma("unroll") for (int _i = 0; _i < 2; ++_i) { unsigned _vo = (voff)[_i]; asm volatile("" : "+v"(_vo));   \
;         __builtin_amdgcn_global_load_lds((const unsigned*)((const char*)(gbase) + _vo), (LAS unsigned*)(lds + (bufoff) + ldsw + _i * 8192), 16, 0, 0); } } while (0)
; #define PG8_WAIT_V(n) asm volatile("s_waitcnt vmcnt(" #n ")" ::: "memory")
; #define PG8_BAR __builtin_amdgcn_s_barrier()
; __device__ __forceinline__ void gemm_phase(LAS unsigned char* lds, const Call& C, const int tid, const Args& args) {
;     ...
;     for (int i = 0; i < 2; ++i) { int R, Cc; stage_rc(tid * 16 + i * 8192, R, Cc); const int Rb = (R & ~31) + perm32(R & 31);
;         voffA[i] = (unsigned)(R * C.lda + Cc) * 2u; voffB[i] = (unsigned)(Rb * C.ldb + Cc) * 2u; }
;     const size_t kstep = (size_t)(BK * 2);
;     const size_t hstepA = (size_t)HALF * C.lda * 2, hstepB = (size_t)HALF * C.ldb * 2;
;     const unsigned ldsw = (unsigned)wid * 1024u;
;     const int aoff = lds_byte(wr * 64 + fr, fq * 8), boff = lds_byte(wc * 32 + fr, fq * 8);
;     ...
;     Unit cur, nxt; int ui = 0;
;     next_unit(C, 0, cur.pm, cur.pn, cur.kp0, cur.np, cur.slice);
;     if (cur.pm < 0) return;
;     f32x4 acc[2][2][4][2];
; #pragma unroll
;     for (int a = 0; a < 2; ++a)
; #pragma unroll
;         for (int b = 0; b < 2; ++b)
; #pragma unroll
;             for (int m = 0; m < 4; ++m)
; #pragma unroll
;                 for (int n = 0; n < 2; ++n) acc[a][b][m][n] = (f32x4){0.f, 0.f, 0.f, 0.f};
;     bf16x8 At[4][2], B0[2][2], B1[2][2];
;     const char* cA = PG8_APTR(cur); const char* cB = PG8_BPTR(cur);
;     PG8_STAGE(PG8_SB(0, 0), cB, voffB); PG8_STAGE(PG8_SB(0, 1), cB + hstepB, voffB); PG8_STAGE(PG8_SA(0, 0), cA, voffA); PG8_STAGE(PG8_SA(0, 1), cA + hstepA, voffA);
;     if (wr == 1) PG8_BAR;
;     PG8_WAIT_V(2); PG8_BAR;
;     PG8_STAGE(PG8_SB(1, 0), cB + kstep, voffB); PG8_STAGE(PG8_SA(1, 0), cA + kstep, voffA); PG8_STAGE(PG8_SB(1, 1), cB + hstepB + kstep, voffB);
.Lp2_skip:
	v_readlane_b32 s24, v254, 19
	v_readlane_b32 s48, v254, 17
	s_cmp_lt_i32 s90, 0
	v_lshlrev_b32_e32 v85, 4, v204
	v_readlane_b32 s4, v254, 11
	v_readlane_b32 s25, v254, 20
	v_readlane_b32 s42, v254, 31
	v_readlane_b32 s44, v254, 39
	v_readlane_b32 s49, v254, 18
	s_cbranch_scc1 .LBB0_502
	v_ashrrev_i32_e32 v1, 31, v85
	v_lshrrev_b32_e32 v1, 22, v1
	v_add_u32_e32 v1, v85, v1
	v_and_b32_e32 v1, 0xfffffc00, v1
	v_sub_u32_e32 v1, v85, v1
	v_ashrrev_i32_e32 v0, 31, v204
	v_lshrrev_b32_e32 v2, 4, v1
	v_lshrrev_b32_e32 v0, 26, v0
	v_bitop3_b32 v2, v2, v1, 32 bitop3:0x6c
	v_ashrrev_i32_e32 v1, 31, v1
	v_add_u32_e32 v0, v204, v0
	v_lshrrev_b32_e32 v1, 26, v1
	v_ashrrev_i32_e32 v0, 6, v0
	v_add_u32_e32 v1, v2, v1
	v_lshlrev_b32_e32 v3, 3, v0
	v_ashrrev_i32_e32 v4, 6, v1
	v_and_b32_e32 v1, 0xc0, v1
	v_and_b32_e32 v3, -16, v3
	v_lshlrev_b32_e32 v0, 5, v0
	v_sub_u32_e32 v1, v2, v1
	v_add_u32_e32 v3, v4, v3
	v_and_b32_e32 v0, 32, v0
	v_ashrrev_i16_sdwa v1, v226, sext(v1) dst_sel:DWORD dst_unused:UNUSED_PAD src0_sel:DWORD src1_sel:BYTE_0
	v_add_u32_sdwa v0, v0, sext(v1) dst_sel:DWORD dst_unused:UNUSED_PAD src0_sel:DWORD src1_sel:WORD_0
	v_lshlrev_b32_e32 v1, 1, v3
	v_lshrrev_b32_e32 v2, 2, v3
	v_and_b32_e32 v4, 3, v4
	s_mov_b32 s4, 0x7fffffe0
	v_and_b32_e32 v1, 24, v1
	v_and_b32_e32 v2, 4, v2
	v_and_or_b32 v4, v3, s4, v4
	v_or3_b32 v1, v4, v2, v1
	v_mul_lo_u32 v2, s52, v3
	v_mul_lo_u32 v1, s52, v1
	v_add_lshl_u32 v205, v2, v0, 1
	v_add_lshl_u32 v242, v1, v0, 1
	v_add_u32_e32 v0, 0x2000, v85
	v_ashrrev_i32_e32 v1, 31, v0
	v_lshrrev_b32_e32 v1, 22, v1
	v_add_u32_e32 v1, v0, v1
	v_ashrrev_i32_e32 v1, 10, v1
	v_mul_i32_i24_e32 v2, 0x400, v1
	v_sub_u32_e32 v0, v0, v2
	v_lshrrev_b32_e32 v2, 4, v0
	v_bitop3_b32 v0, v2, v0, 32 bitop3:0x6c
	v_ashrrev_i32_e32 v3, 31, v0
	v_writelane_b32 v254, s51, 52
	v_lshrrev_b32_e32 v3, 26, v3
	v_writelane_b32 v254, s88, 53
	v_lshlrev_b32_e32 v2, 3, v1
	v_add_u32_e32 v3, v0, v3
	v_writelane_b32 v254, s89, 54
	v_and_b32_e32 v2, -16, v2
	v_ashrrev_i32_e32 v4, 6, v3
	v_writelane_b32 v254, s90, 55
	v_add_u32_e32 v2, v4, v2
	v_and_b32_e32 v4, 3, v4
	v_writelane_b32 v254, s91, 56
	s_ashr_i32 s12, s5, 6
	v_and_or_b32 v4, v2, s4, v4
	s_lshl_b32 s22, s52, 8
	s_mov_b32 s53, s29
	s_lshl_b32 s4, s90, 1
	s_ashr_i32 s13, s5, 8
	s_lshl_b64 s[74:75], s[52:53], 8
	s_lshl_b32 s23, s12, 10
	s_mul_hi_u32 s8, s4, s22
	s_mul_i32 s4, s4, s22
	v_readlane_b32 s34, v254, 25
	v_readlane_b32 s35, v254, 26
	s_add_u32 s4, s34, s4
	s_addc_u32 s14, s35, s8
	s_ashr_i32 s8, s78, 31
	s_lshl_b64 s[76:77], s[52:53], 9
	v_and_b32_e32 v3, 0xc0, v3
	s_mul_i32 s8, s76, s8
	s_mul_hi_u32 s9, s76, s78
	v_lshlrev_b32_e32 v1, 5, v1
	v_sub_u32_e32 v0, v0, v3
	s_add_i32 s8, s9, s8
	s_lshr_b32 s9, s52, 23
	v_and_b32_e32 v1, 32, v1
	v_ashrrev_i16_sdwa v0, v226, sext(v0) dst_sel:DWORD dst_unused:UNUSED_PAD src0_sel:DWORD src1_sel:BYTE_0
	s_mul_i32 s9, s9, s78
	v_add_u32_sdwa v0, v1, sext(v0) dst_sel:DWORD dst_unused:UNUSED_PAD src0_sel:DWORD src1_sel:WORD_0
	v_lshlrev_b32_e32 v1, 1, v2
	v_lshrrev_b32_e32 v3, 2, v2
	s_add_i32 s8, s8, s9
	s_mul_i32 s9, s76, s78
	v_and_b32_e32 v1, 24, v1
	v_and_b32_e32 v3, 4, v3
	s_add_u32 s9, s24, s9
	v_or3_b32 v1, v4, v3, v1
	s_addc_u32 s17, s25, s8
	v_mul_lo_u32 v2, s52, v2
	v_mul_lo_u32 v1, s52, v1
	s_add_u32 s8, s9, s0
	v_add_lshl_u32 v243, v2, v0, 1
	v_add_lshl_u32 v244, v1, v0, 1
	s_addc_u32 s9, s17, s1
	s_add_i32 s20, s23, 0
	v_mov_b32_e32 v0, v242
	s_add_i32 m0, s20, 0x10000
	s_nop 0
	global_load_lds_dwordx4 v0, s[8:9]
	v_mov_b32_e32 v0, v244
	s_add_i32 m0, s20, 0x12000
	s_add_u32 s34, s8, s74
	global_load_lds_dwordx4 v0, s[8:9]
	v_mov_b32_e32 v0, v242
	s_addc_u32 s35, s9, s75
	s_add_i32 m0, s20, 0x14000
	s_nop 0
	global_load_lds_dwordx4 v0, s[34:35]
	v_mov_b32_e32 v0, v244
	s_add_i32 m0, s20, 0x16000
	s_add_u32 s0, s4, s0
	global_load_lds_dwordx4 v0, s[34:35]
	v_mov_b32_e32 v0, v205
	s_addc_u32 s1, s14, s1
	s_mov_b32 m0, s20
	s_add_i32 s72, s20, 0x2000
	global_load_lds_dwordx4 v0, s[0:1]
	v_mov_b32_e32 v0, v243
	s_mov_b32 m0, s72
	s_add_u32 s24, s0, s22
	global_load_lds_dwordx4 v0, s[0:1]
	s_addc_u32 s25, s1, 0
	s_add_i32 s73, s20, 0x4000
	v_mov_b32_e32 v0, v205
	s_mov_b32 m0, s73
	s_add_i32 s4, s20, 0x6000
	global_load_lds_dwordx4 v0, s[24:25]
	v_mov_b32_e32 v0, v243
	s_mov_b32 m0, s4
	s_cmp_eq_u32 s13, 1
	global_load_lds_dwordx4 v0, s[24:25]
	s_cselect_b64 s[24:25], -1, 0
	v_writelane_b32 v254, s24, 57
	v_mov_b32_e32 v80, v242
	s_add_i32 m0, s20, 0x18000
	v_lshl_add_u64 v[0:1], s[8:9], 0, v[80:81]
	v_lshl_add_u64 v[0:1], v[0:1], 0, s[18:19]
	v_mov_b32_e32 v80, v244
	global_load_lds_dwordx4 v[0:1], off
	s_add_i32 m0, s20, 0x1a000
	v_lshl_add_u64 v[0:1], s[8:9], 0, v[80:81]
	v_lshl_add_u64 v[0:1], v[0:1], 0, s[18:19]
	v_mov_b32_e32 v80, v205
	global_load_lds_dwordx4 v[0:1], off
	s_add_i32 s14, s20, 0x8000
	v_lshl_add_u64 v[0:1], s[0:1], 0, v[80:81]
	v_lshl_add_u64 v[0:1], v[0:1], 0, s[18:19]
	s_mov_b32 m0, s14
	v_mov_b32_e32 v80, v243
	global_load_lds_dwordx4 v[0:1], off
	s_add_i32 s52, s20, 0xa000
	v_lshl_add_u64 v[0:1], s[0:1], 0, v[80:81]
	v_lshl_add_u64 v[0:1], v[0:1], 0, s[18:19]
	s_mov_b32 m0, s52
	v_mov_b32_e32 v80, v242
	s_nop 0
	global_load_lds_dwordx4 v[0:1], off
	v_lshl_add_u64 v[0:1], s[34:35], 0, v[80:81]
	s_add_i32 m0, s20, 0x1c000
	v_lshl_add_u64 v[0:1], v[0:1], 0, s[18:19]
	s_nop 0
	global_load_lds_dwordx4 v[0:1], off
	s_cmp_lg_u32 s13, 1
	s_nop 0
	v_writelane_b32 v254, s25, 58
	s_cbranch_scc1 .LBB0_264
	s_barrier
; #define PG8_STAGE(bufoff, gbase, voff) do { _Pragma("unroll") for (int _i = 0; _i < 2; ++_i) { unsigned _vo = (voff)[_i]; asm volatile("" : "+v"(_vo));   \
;         __builtin_amdgcn_global_load_lds((const unsigned*)((const char*)(gbase) + _vo), (LAS unsigned*)(lds + (bufoff) + ldsw + _i * 8192), 16, 0, 0); } } while (0)
; #define PG8_WAIT_V(n) asm volatile("s_waitcnt vmcnt(" #n ")" ::: "memory")
; #define PG8_BAR __builtin_amdgcn_s_barrier()
; __device__ __forceinline__ void gemm_phase(LAS unsigned char* lds, const Call& C, const int tid, const Args& args) {
;     ...
;     PG8_STAGE(PG8_SB(0, 0), cB, voffB); PG8_STAGE(PG8_SB(0, 1), cB + hstepB, voffB); PG8_STAGE(PG8_SA(0, 0), cA, voffA); PG8_STAGE(PG8_SA(0, 1), cA + hstepA, voffA);
;     if (wr == 1) PG8_BAR;
;     PG8_WAIT_V(2); PG8_BAR;
;     PG8_STAGE(PG8_SB(1, 0), cB + kstep, voffB); PG8_STAGE(PG8_SA(1, 0), cA + kstep, voffA); PG8_STAGE(PG8_SB(1, 1), cB + hstepB + kstep, voffB);
;     PG8_WAIT_V(6); PG8_BAR;
;     for (;;) {
;         next_unit(C, ui + 1, nxt.pm, nxt.pn, nxt.kp0, nxt.np, nxt.slice);
;         const bool has_next = nxt.pm >= 0;
;         const char* nA = has_next ? PG8_APTR(nxt) : cA; const char* nB = has_next ? PG8_BPTR(nxt) : cB;
;         const int nt = 2 * cur.np;
.LBB0_264:
	v_mov_b32_e32 v80, v242
	s_waitcnt vmcnt(7)
	s_barrier
	s_and_b32 s24, s12, 3
	s_lshl_b32 s27, s13, 6
	s_lshl_b32 s17, s13, 13
	s_lshl_b32 s13, s24, 5
	s_nop 0
	v_writelane_b32 v254, s13, 59
	s_lshl_b32 s13, s24, 12
	v_mov_b32_e32 v80, v242
	s_add_i32 m0, s20, 0x1e000
	s_cmpk_lt_u32 s5, 0x100
	v_mov_b32_e32 v80, v244
	s_cselect_b64 s[80:81], -1, 0
	s_bitcmp0_b32 s5, 6
	s_mov_b32 s97, s29
	v_lshl_add_u64 v[0:1], s[34:35], 0, v[80:81]
	s_cselect_b64 s[34:35], -1, 0
	s_lshl_b32 s25, s24, 4
	v_writelane_b32 v254, s34, 60
	s_add_i32 s25, s25, 0
	s_add_i32 s25, s25, 0x20400
	v_writelane_b32 v254, s35, 61
	s_lshl_b32 s12, s12, 5
	v_writelane_b32 v254, s25, 62
	s_cmp_lt_u32 s5, 64
	v_writelane_b32 v254, s12, 63
	s_cselect_b64 s[34:35], -1, 0
	v_writelane_b32 v255, s34, 0
	s_ashr_i32 s53, s11, 31
	s_ashr_i32 s51, s21, 31
	v_readlane_b32 s47, v254, 38
	s_lshl_b32 s12, s24, 6
	v_readlane_b32 s24, v254, 23
	v_writelane_b32 v255, s35, 1
	s_mul_i32 s5, s47, s42
	v_readlane_b32 s25, v254, 24
	s_add_u32 s12, s24, s12
	v_readlane_b32 s43, v254, 16
	v_writelane_b32 v255, s12, 2
	s_addc_u32 s12, s25, 0
	s_mul_i32 s5, s5, s43
	v_writelane_b32 v255, s12, 3
	s_add_i32 s54, s5, s26
	s_lshr_b32 s5, s26, 3
	s_and_b32 s88, s26, 7
	v_writelane_b32 v255, s5, 4
	s_add_i32 s5, s5, 1
	s_lshl_b32 s45, s43, 2
	s_add_u32 s24, s48, 0x1000
	v_writelane_b32 v255, s5, 5
	s_addc_u32 s25, s49, 0
	v_writelane_b32 v255, s24, 6
	v_readlane_b32 s5, v254, 52
	s_add_i32 s5, s27, s5
	v_writelane_b32 v255, s25, 7
	v_writelane_b32 v255, s27, 8
	v_writelane_b32 v255, s5, 9
	s_ashr_i32 s5, s44, 1
	v_lshl_add_u64 v[0:1], v[0:1], 0, s[18:19]
	s_and_b32 s12, s44, 1
	s_bfe_i32 s28, s44, 0x10000
	s_lshl_b32 s24, s5, 3
	global_load_lds_dwordx4 v[0:1], off
	s_bitcmp1_b32 s44, 0
	v_writelane_b32 v255, s24, 10
	s_cselect_b64 s[24:25], -1, 0
	s_cmp_lg_u32 s5, 3
	s_cselect_b64 s[34:35], -1, 0
	s_cmp_eq_u32 s12, 0
	s_cselect_b64 s[36:37], -1, 0
	s_and_b64 s[38:39], s[36:37], exec
	s_movk_i32 s12, 0x1400
	s_movk_i32 s27, 0xc00
	s_cselect_b32 s12, 0x800, s12
	s_cselect_b32 s38, 0x400, s27
	s_cselect_b32 s39, s94, 0x400
	s_cselect_b32 s40, 0xc00, 0
	s_cselect_b32 s41, 0x800, 0
	s_or_b64 s[34:35], s[36:37], s[34:35]
	v_writelane_b32 v255, s34, 11
	s_lshl_b32 s27, s44, 12
	s_mov_b32 s55, s29
	v_writelane_b32 v255, s35, 12
	s_xor_b64 s[34:35], s[34:35], -1
	v_writelane_b32 v255, s34, 13
	s_waitcnt vmcnt(6)
	s_mov_b32 s92, 0
	s_movk_i32 s46, 0x1600
	v_writelane_b32 v255, s35, 14
	s_lshl_b32 s34, s5, 12
	s_or_b32 s34, s38, s34
	s_ashr_i32 s35, s34, 31
	s_lshl_b64 s[34:35], s[34:35], 2
	s_add_u32 s34, s68, s34
	v_writelane_b32 v255, s27, 15
	s_addc_u32 s35, s69, s35
	s_and_b32 s27, s28, 0x30000
	v_writelane_b32 v255, s34, 16
	s_cmp_lt_i32 s5, 3
	s_barrier
	v_writelane_b32 v255, s35, 17
	s_cselect_b64 s[34:35], -1, 0
	s_and_b64 s[24:25], s[24:25], s[34:35]
	v_cndmask_b32_e64 v2, 0, 1, s[24:25]
	v_writelane_b32 v255, s27, 18
	v_readfirstlane_b32 s24, v2
	s_add_i32 s5, s5, s24
	s_lshl_b32 s5, s5, 12
	v_cvt_f32_u32_e32 v2, s42
	s_or_b32 s24, s5, s41
	s_ashr_i32 s25, s24, 31
	s_lshl_b64 s[24:25], s[24:25], 2
	s_add_u32 s24, s68, s24
	v_rcp_iflag_f32_e32 v3, v2
	s_addc_u32 s25, s69, s25
	v_writelane_b32 v255, s24, 19
	v_readlane_b32 s27, v254, 41
	v_mul_f32_e32 v4, 0x4f7ffffe, v3
	v_writelane_b32 v255, s25, 20
	s_add_u32 s24, s48, 0x2c00
	s_addc_u32 s25, s49, 0
	v_writelane_b32 v255, s24, 21
	v_cvt_u32_f32_e32 v4, v4
	s_nop 0
	v_writelane_b32 v255, s25, 22
	s_add_u32 s24, s48, 0x5800
	s_addc_u32 s25, s49, 0
	v_writelane_b32 v255, s24, 23
	s_sub_i32 s5, 0, s42
	s_lshl_b32 s96, s43, 8
	v_writelane_b32 v255, s25, 24
	v_readfirstlane_b32 s24, v4
	v_cvt_f32_u32_e32 v4, s27
	s_mul_i32 s5, s5, s24
	s_mul_hi_u32 s5, s24, s5
	s_add_i32 s5, s24, s5
	v_mul_f32_e32 v3, v4, v3
	v_trunc_f32_e32 v3, v3
	v_fma_f32 v4, -v3, v2, v4
	v_cvt_u32_f32_e32 v3, v3
	v_writelane_b32 v255, s5, 25
	s_lshl_b64 s[82:83], s[96:97], 8
	v_cmp_ge_f32_e64 s[24:25], |v4|, v2
	v_and_b32_e32 v2, 48, v204
	v_lshlrev_b32_e32 v4, 6, v204
	s_movk_i32 s5, 0x3c0
	s_cmp_lg_u64 s[24:25], 0
	v_and_or_b32 v2, v4, s5, v2
	v_readfirstlane_b32 s5, v3
	s_addc_u32 s5, s5, 0
	s_abs_i32 s97, s43
	v_cvt_f32_u32_e32 v3, s97
	v_lshlrev_b32_e32 v4, 2, v204
	v_and_b32_e32 v4, 32, v4
	s_abs_i32 s93, s45
	v_bitop3_b32 v5, v2, s17, v4 bitop3:0xde
	v_rcp_iflag_f32_e32 v3, v3
	v_bitop3_b32 v245, s13, v2, v4 bitop3:0xf6
	v_cvt_f32_u32_e32 v2, s93
	s_sub_i32 s13, 0, s97
	v_mul_f32_e32 v3, 0x4f7ffffe, v3
	v_cvt_u32_f32_e32 v3, v3
	v_rcp_iflag_f32_e32 v2, v2
	s_and_b32 s5, s5, 31
	v_add_u32_e32 v246, 0, v5
	v_readfirstlane_b32 s17, v3
	v_mul_f32_e32 v2, 0x4f7ffffe, v2
	v_cvt_u32_f32_e32 v2, v2
	s_mul_i32 s13, s13, s17
	s_mul_hi_u32 s13, s17, s13
	s_add_i32 s13, s17, s13
	v_writelane_b32 v255, s13, 26
	s_sub_i32 s13, 0, s93
	v_readfirstlane_b32 s17, v2
	s_mul_i32 s13, s13, s17
	s_mul_hi_u32 s13, s17, s13
	v_writelane_b32 v255, s45, 27
	s_add_i32 s13, s17, s13
	v_writelane_b32 v255, s13, 28
	v_writelane_b32 v255, s5, 29
	s_mul_i32 s5, s5, s42
	s_sub_i32 s5, s27, s5
	v_writelane_b32 v255, s5, 30
	s_ashr_i32 s5, s43, 31
	v_writelane_b32 v255, s5, 31
	s_bfe_i32 s5, s43, 0x1001d
	v_writelane_b32 v255, s5, 32
	s_add_u32 s89, s22, 0x80
	v_writelane_b32 v255, s54, 33
	s_addc_u32 s94, 0, 0
	s_lshl_b32 s5, s12, 2
	v_writelane_b32 v255, s55, 34
	v_writelane_b32 v255, s5, 35
	s_lshl_b32 s12, s40, 2
	v_writelane_b32 v255, s12, 36
	s_lshl_b32 s28, s39, 2
	s_mov_b32 s27, s29
	v_writelane_b32 v255, s13, 37
	v_readlane_b32 s55, v254, 15
	s_branch .LBB0_267
